# Gray MFMA order + residual epilogue: second-half residual loads hoisted behind first-half loads
# baseline (speedup 1.0000x reference)
; #define GAS __attribute__((address_space(1)))
;     __device__ __forceinline__ void operator()(const f32x4 (&acc)[2][2][4][2], const Unit& u, int wr, int wc, int fr, int fq, int ui) const {
;     ...
;         for (int ai = 0; ai < 2; ++ai) {
;             u32x4 xb[4][2];
; #pragma unroll
;             for (int m = 0; m < 4; ++m)
; #pragma unroll
;                 for (int bj = 0; bj < 2; ++bj) xb[m][bj] = *(const GAS u32x4*)(XB + ((size_t)(2 * u.pm + ai) * 32 + 8 * u.pn + 4 * bj + wc) * 4096 + (wr * 64 + m * 16 + fr) * 32 + 8 * fq);
; #pragma unroll
;             for (int m = 0; m < 4; ++m) {
;                 const int row = row0 + ai * HALF + m * 16;
;                 float ss = 0.f;
; #pragma unroll
;                 for (int bj = 0; bj < 2; ++bj) {
;                     const u32x4 b = xb[m][bj];
;                     const f32x4 a0 = {__builtin_bit_cast(float, b.x << 16), __builtin_bit_cast(float, b.x & 0xffff0000u), __builtin_bit_cast(float, b.y << 16), __builtin_bit_cast(float, b.y & 0xffff0000u)};
;                     const f32x4 a1 = {__builtin_bit_cast(float, b.z << 16), __builtin_bit_cast(float, b.z & 0xffff0000u), __builtin_bit_cast(float, b.w << 16), __builtin_bit_cast(float, b.w & 0xffff0000u)};
;                     const f32x4 o0 = a0 + acc[ai][bj][m][0] * scale, o1 = a1 + acc[ai][bj][m][1] * scale;
;                     { const f32x4 q = o0 * o0 + o1 * o1; ss += (q[0] + q[1]) + (q[2] + q[3]); }
;                     u32x4 w; w.x = pk_bf16(o0[0], o0[1]); w.y = pk_bf16(o0[2], o0[3]); w.z = pk_bf16(o1[0], o1[1]); w.w = pk_bf16(o1[2], o1[3]);
;                     *(GAS u32x4*)(XBo + ((size_t)(2 * u.pm + ai) * 32 + 8 * u.pn + 4 * bj + wc) * 4096 + (wr * 64 + m * 16 + fr) * 32 + 8 * fq) = w;
;                 }
;                 { const unsigned sb = __builtin_bit_cast(unsigned, ss); auto r16 = __builtin_amdgcn_permlane16_swap(sb, sb, false, false);
;                   ss = __builtin_bit_cast(float, (unsigned)r16[0]) + __builtin_bit_cast(float, (unsigned)r16[1]);
;                   const unsigned sc = __builtin_bit_cast(unsigned, ss); auto r32 = __builtin_amdgcn_permlane32_swap(sc, sc, false, false);
;                   ss = __builtin_bit_cast(float, (unsigned)r32[0]) + __builtin_bit_cast(float, (unsigned)r32[1]); }
;                 if (fq == 0) ((GAS float*)SSP)[(size_t)row * 16 + u.pn * 4 + wc] = ss;
.LBB0_313:
	s_lshl_b32 s2, s34, 3
	s_lshl_b32 s24, s46, 1
	s_ashr_i32 s3, s2, 31
	s_or_b64 s[26:27], s[2:3], s[40:41]
	s_lshl_b32 s2, s34, 2
	s_ashr_i32 s25, s24, 31
	v_lshl_add_u32 v184, s46, 8, v186
	s_ashr_i32 s3, s2, 31
	s_lshl_b64 s[48:49], s[24:25], 18
	s_lshl_b64 s[46:47], s[26:27], 13
	s_add_u32 s48, s48, s46
	s_addc_u32 s49, s49, s47
	v_lshl_add_u64 v[130:131], v[168:169], 0, s[48:49]
	global_load_dwordx4 v[206:209], v[130:131], off
	s_or_b32 s26, s48, 0x8000
	s_mov_b32 s27, s49
	v_lshl_add_u64 v[132:133], v[168:169], 0, s[26:27]
	global_load_dwordx4 v[210:213], v[132:133], off
	global_load_dwordx4 v[150:153], v[130:131], off offset:1024
	v_lshl_add_u64 v[132:133], v[170:171], 0, s[26:27]
	global_load_dwordx4 v[146:149], v[132:133], off
	global_load_dwordx4 v[142:145], v[130:131], off offset:2048
	v_lshl_add_u64 v[132:133], v[172:173], 0, s[26:27]
	global_load_dwordx4 v[138:141], v[132:133], off
	global_load_dwordx4 v[134:137], v[130:131], off offset:3072
	v_lshl_add_u64 v[130:131], v[174:175], 0, s[26:27]
	global_load_dwordx4 v[130:133], v[130:131], off
	s_add_u32 s66, s48, 0x40000
	s_addc_u32 s67, s49, 0
	v_lshl_add_u64 v[248:249], v[168:169], 0, s[66:67]
	global_load_dwordx4 v[240:243], v[248:249], off
	s_or_b32 s66, s66, 0x8000
	v_lshl_add_u64 v[250:251], v[168:169], 0, s[66:67]
	global_load_dwordx4 v[244:247], v[250:251], off
	global_load_dwordx4 v[236:239], v[248:249], off offset:1024
	v_lshl_add_u64 v[250:251], v[170:171], 0, s[66:67]
	global_load_dwordx4 v[232:235], v[250:251], off
	global_load_dwordx4 v[228:231], v[248:249], off offset:2048
	v_lshl_add_u64 v[250:251], v[172:173], 0, s[66:67]
	global_load_dwordx4 v[224:227], v[250:251], off
	global_load_dwordx4 v[220:223], v[248:249], off offset:3072
	v_lshl_add_u64 v[250:251], v[174:175], 0, s[66:67]
	global_load_dwordx4 v[216:219], v[250:251], off
	v_mov_b32_e32 v167, v166
	s_waitcnt vmcnt(8)
	v_lshlrev_b32_e32 v190, 16, v206
	v_and_b32_e32 v191, 0xffff0000, v206
	v_lshlrev_b32_e32 v214, 16, v208
	v_and_b32_e32 v215, 0xffff0000, v208
	v_lshlrev_b32_e32 v208, 16, v209
	v_and_b32_e32 v209, 0xffff0000, v209
	v_lshlrev_b32_e32 v206, 16, v207
	v_and_b32_e32 v207, 0xffff0000, v207
	v_pk_fma_f32 v[126:127], v[126:127], v[176:177], v[190:191]
	v_pk_fma_f32 v[190:191], v[124:125], v[166:167], v[208:209]
	v_pk_fma_f32 v[122:123], v[122:123], v[176:177], v[214:215]
	v_pk_fma_f32 v[128:129], v[128:129], v[166:167], v[206:207]
	v_pk_mul_f32 v[124:125], v[122:123], v[122:123]
	v_pk_mul_f32 v[206:207], v[190:191], v[190:191]
	v_pk_fma_f32 v[124:125], v[126:127], v[126:127], v[124:125]
	v_pk_fma_f32 v[206:207], v[128:129], v[128:129], v[206:207]
	v_add_f32_e32 v124, v124, v125
	v_add_f32_e32 v125, v206, v207
	v_add_f32_e32 v185, v124, v125
	v_cvt_pk_bf16_f32 v124, v126, v127
	v_cvt_pk_bf16_f32 v125, v128, v129
	v_cvt_pk_bf16_f32 v126, v122, v123
	v_cvt_pk_bf16_f32 v127, v190, v191
	v_lshl_add_u64 v[122:123], v[178:179], 0, s[48:49]
	global_store_dwordx4 v[122:123], v[124:127], off
	v_lshlrev_b32_e32 v128, 16, v212
	v_and_b32_e32 v129, 0xffff0000, v212
	v_lshlrev_b32_e32 v124, 16, v210
	v_and_b32_e32 v125, 0xffff0000, v210
	v_lshlrev_b32_e32 v190, 16, v213
	v_and_b32_e32 v191, 0xffff0000, v213
	v_lshlrev_b32_e32 v126, 16, v211
	v_and_b32_e32 v127, 0xffff0000, v211
	v_pk_fma_f32 v[118:119], v[118:119], v[176:177], v[124:125]
	v_pk_fma_f32 v[124:125], v[116:117], v[166:167], v[190:191]
	v_pk_fma_f32 v[116:117], v[114:115], v[176:177], v[128:129]
	v_pk_fma_f32 v[120:121], v[120:121], v[166:167], v[126:127]
	v_pk_mul_f32 v[114:115], v[116:117], v[116:117]
	v_pk_mul_f32 v[126:127], v[124:125], v[124:125]
	v_pk_fma_f32 v[114:115], v[118:119], v[118:119], v[114:115]
	v_pk_fma_f32 v[126:127], v[120:121], v[120:121], v[126:127]
	v_add_f32_e32 v114, v114, v115
	v_add_f32_e32 v115, v126, v127
	v_add_f32_e32 v114, v114, v115
	v_add_f32_e32 v126, v185, v114
	v_cvt_pk_bf16_f32 v114, v118, v119
	v_cvt_pk_bf16_f32 v115, v120, v121
	v_cvt_pk_bf16_f32 v116, v116, v117
	v_cvt_pk_bf16_f32 v117, v124, v125
	v_lshl_add_u64 v[118:119], v[178:179], 0, s[26:27]
	global_store_dwordx4 v[118:119], v[114:117], off
	v_ashrrev_i32_e32 v185, 31, v184
	s_nop 0
	v_mov_b32_e32 v114, v126
	s_nop 1
	v_permlane16_swap_b32_e32 v126, v114
	v_add_f32_e32 v114, v126, v114
	v_mov_b32_e32 v115, v114
	s_nop 1
	v_permlane32_swap_b32_e32 v114, v115
	s_and_saveexec_b64 s[26:27], s[4:5]
	s_cbranch_execz .LBB0_315
	v_add_f32_e32 v116, v114, v115
	v_lshlrev_b64 v[114:115], 6, v[184:185]
	v_lshl_add_u64 v[114:115], s[22:23], 0, v[114:115]
	v_lshl_add_u64 v[114:115], s[2:3], 2, v[114:115]
	s_lshl_b32 s34, s40, 2
	v_lshl_add_u64 v[114:115], v[114:115], 0, s[34:35]
	global_store_dword v[114:115], v116, off

; #define GAS __attribute__((address_space(1)))
; __device__ __forceinline__ unsigned pk_bf16(float lo, float hi) { typedef __bf16 bf2 __attribute__((ext_vector_type(2))); f32x2 v = {lo, hi}; bf2 b = __builtin_convertvector(v, bf2); return __builtin_bit_cast(unsigned, b); }
;     __device__ __forceinline__ void operator()(const f32x4 (&acc)[2][2][4][2], const Unit& u, int wr, int wc, int fr, int fq, int ui) const {
;     ...
;             for (int m = 0; m < 4; ++m) {
;                 const int row = row0 + ai * HALF + m * 16;
;                 float ss = 0.f;
; #pragma unroll
;                 for (int bj = 0; bj < 2; ++bj) {
;                     const u32x4 b = xb[m][bj];
;                     const f32x4 a0 = {__builtin_bit_cast(float, b.x << 16), __builtin_bit_cast(float, b.x & 0xffff0000u), __builtin_bit_cast(float, b.y << 16), __builtin_bit_cast(float, b.y & 0xffff0000u)};
;                     const f32x4 a1 = {__builtin_bit_cast(float, b.z << 16), __builtin_bit_cast(float, b.z & 0xffff0000u), __builtin_bit_cast(float, b.w << 16), __builtin_bit_cast(float, b.w & 0xffff0000u)};
;                     const f32x4 o0 = a0 + acc[ai][bj][m][0] * scale, o1 = a1 + acc[ai][bj][m][1] * scale;
;                     { const f32x4 q = o0 * o0 + o1 * o1; ss += (q[0] + q[1]) + (q[2] + q[3]); }
;                     u32x4 w; w.x = pk_bf16(o0[0], o0[1]); w.y = pk_bf16(o0[2], o0[3]); w.z = pk_bf16(o1[0], o1[1]); w.w = pk_bf16(o1[2], o1[3]);
;                     *(GAS u32x4*)(XBo + ((size_t)(2 * u.pm + ai) * 32 + 8 * u.pn + 4 * bj + wc) * 4096 + (wr * 64 + m * 16 + fr) * 32 + 8 * fq) = w;
;                 }
;                 { const unsigned sb = __builtin_bit_cast(unsigned, ss); auto r16 = __builtin_amdgcn_permlane16_swap(sb, sb, false, false);
;                   ss = __builtin_bit_cast(float, (unsigned)r16[0]) + __builtin_bit_cast(float, (unsigned)r16[1]);
;                   const unsigned sc = __builtin_bit_cast(unsigned, ss); auto r32 = __builtin_amdgcn_permlane32_swap(sc, sc, false, false);
;                   ss = __builtin_bit_cast(float, (unsigned)r32[0]) + __builtin_bit_cast(float, (unsigned)r32[1]); }
;                 if (fq == 0) ((GAS float*)SSP)[(size_t)row * 16 + u.pn * 4 + wc] = ss;
.LBB0_321:
	s_or_b64 exec, exec, s[26:27]
	s_or_b32 s24, s24, 1
	s_ashr_i32 s25, s24, 31
	s_lshl_b64 s[24:25], s[24:25], 18
	s_add_u32 s26, s24, s46
	s_addc_u32 s27, s25, s47
	s_or_b32 s24, s26, 0x8000
	s_mov_b32 s25, s27
	v_mov_b32_e32 v167, v166
	s_waitcnt vmcnt(8)
	v_lshlrev_b32_e32 v98, 16, v240
	v_and_b32_e32 v99, 0xffff0000, v240
	v_lshlrev_b32_e32 v240, 16, v241
	v_and_b32_e32 v241, 0xffff0000, v241
	v_lshlrev_b32_e32 v100, 16, v242
	v_and_b32_e32 v101, 0xffff0000, v242
	v_lshlrev_b32_e32 v242, 16, v243
	v_and_b32_e32 v243, 0xffff0000, v243
	v_pk_fma_f32 v[64:65], v[64:65], v[166:167], v[240:241]
	v_pk_fma_f32 v[240:241], v[60:61], v[166:167], v[242:243]
	v_pk_fma_f32 v[58:59], v[58:59], v[176:177], v[100:101]
	v_pk_fma_f32 v[62:63], v[62:63], v[176:177], v[98:99]
	v_pk_mul_f32 v[60:61], v[58:59], v[58:59]
	v_pk_mul_f32 v[242:243], v[240:241], v[240:241]
	v_pk_fma_f32 v[60:61], v[62:63], v[62:63], v[60:61]
	v_pk_fma_f32 v[242:243], v[64:65], v[64:65], v[242:243]
	v_add_f32_e32 v60, v60, v61
	v_add_f32_e32 v61, v242, v243
	v_add_f32_e32 v242, v60, v61
	v_cvt_pk_bf16_f32 v60, v62, v63
	v_cvt_pk_bf16_f32 v61, v64, v65
	v_cvt_pk_bf16_f32 v62, v58, v59
	v_cvt_pk_bf16_f32 v63, v240, v241
	v_lshl_add_u64 v[58:59], v[178:179], 0, s[26:27]
	global_store_dwordx4 v[58:59], v[60:63], off
	v_lshlrev_b32_e32 v64, 16, v246
	v_and_b32_e32 v65, 0xffff0000, v246
	v_lshlrev_b32_e32 v60, 16, v244
	v_and_b32_e32 v61, 0xffff0000, v244
	v_lshlrev_b32_e32 v240, 16, v247
	v_and_b32_e32 v241, 0xffff0000, v247
	v_lshlrev_b32_e32 v62, 16, v245
	v_and_b32_e32 v63, 0xffff0000, v245
	v_pk_fma_f32 v[54:55], v[54:55], v[176:177], v[60:61]
	v_pk_fma_f32 v[60:61], v[52:53], v[166:167], v[240:241]
	v_pk_fma_f32 v[52:53], v[50:51], v[176:177], v[64:65]
	v_pk_fma_f32 v[56:57], v[56:57], v[166:167], v[62:63]
	v_pk_mul_f32 v[50:51], v[52:53], v[52:53]
	v_pk_mul_f32 v[62:63], v[60:61], v[60:61]
	v_pk_fma_f32 v[50:51], v[54:55], v[54:55], v[50:51]
	v_pk_fma_f32 v[62:63], v[56:57], v[56:57], v[62:63]
	v_add_f32_e32 v50, v50, v51
	v_add_f32_e32 v51, v62, v63
	v_add_f32_e32 v50, v50, v51
	v_add_f32_e32 v62, v242, v50
	v_cvt_pk_bf16_f32 v50, v54, v55
	v_cvt_pk_bf16_f32 v51, v56, v57
	v_cvt_pk_bf16_f32 v52, v52, v53
	v_cvt_pk_bf16_f32 v53, v60, v61
	v_lshl_add_u64 v[54:55], v[178:179], 0, s[24:25]
	global_store_dwordx4 v[54:55], v[50:53], off
	s_nop 1
	v_mov_b32_e32 v50, v62
	s_nop 1
	v_permlane16_swap_b32_e32 v62, v50
	v_add_f32_e32 v50, v62, v50
	v_mov_b32_e32 v51, v50
	s_nop 1
	v_permlane32_swap_b32_e32 v50, v51
	s_and_saveexec_b64 s[24:25], s[4:5]
	s_cbranch_execz .LBB0_323
	v_add_f32_e32 v52, v50, v51
	v_lshlrev_b64 v[50:51], 6, v[184:185]
	v_lshl_add_u64 v[50:51], s[22:23], 0, v[50:51]
	v_lshl_add_u64 v[50:51], s[2:3], 2, v[50:51]
	s_lshl_b32 s34, s40, 2
	v_lshl_add_u64 v[50:51], v[50:51], 0, s[34:35]
	v_add_co_u32_e32 v50, vcc, 0x2000, v50
	s_nop 1
	v_addc_co_u32_e32 v51, vcc, 0, v51, vcc
	global_store_dword v[50:51], v52, off
.LBB0_323:
	s_or_b64 exec, exec, s[24:25]
	v_lshlrev_b32_e32 v50, 16, v236
	v_and_b32_e32 v51, 0xffff0000, v236
	v_lshlrev_b32_e32 v56, 16, v238
	v_and_b32_e32 v57, 0xffff0000, v238
	v_lshlrev_b32_e32 v60, 16, v239
	v_and_b32_e32 v61, 0xffff0000, v239
	v_lshlrev_b32_e32 v52, 16, v237
	v_and_b32_e32 v53, 0xffff0000, v237
	v_pk_fma_f32 v[46:47], v[46:47], v[176:177], v[50:51]
	v_pk_fma_f32 v[50:51], v[44:45], v[166:167], v[60:61]
	v_pk_fma_f32 v[44:45], v[42:43], v[176:177], v[56:57]
	v_pk_fma_f32 v[48:49], v[48:49], v[166:167], v[52:53]
	v_pk_mul_f32 v[42:43], v[44:45], v[44:45]
	v_pk_mul_f32 v[52:53], v[50:51], v[50:51]
	v_pk_fma_f32 v[42:43], v[46:47], v[46:47], v[42:43]
	v_pk_fma_f32 v[52:53], v[48:49], v[48:49], v[52:53]
	v_add_f32_e32 v42, v42, v43
	v_add_f32_e32 v43, v52, v53
	v_add_f32_e32 v52, v42, v43
	v_cvt_pk_bf16_f32 v42, v46, v47
	v_cvt_pk_bf16_f32 v43, v48, v49
	v_cvt_pk_bf16_f32 v44, v44, v45
	v_cvt_pk_bf16_f32 v45, v50, v51
	global_store_dwordx4 v[58:59], v[42:45], off offset:1024
	v_lshlrev_b32_e32 v46, 16, v234
	v_and_b32_e32 v47, 0xffff0000, v234
	v_lshlrev_b32_e32 v42, 16, v232
	v_and_b32_e32 v43, 0xffff0000, v232
	v_lshlrev_b32_e32 v48, 16, v235
	v_and_b32_e32 v49, 0xffff0000, v235
	v_lshlrev_b32_e32 v44, 16, v233
	v_and_b32_e32 v45, 0xffff0000, v233
	v_pk_fma_f32 v[38:39], v[38:39], v[176:177], v[42:43]
	v_pk_fma_f32 v[42:43], v[36:37], v[166:167], v[48:49]
	v_pk_fma_f32 v[36:37], v[34:35], v[176:177], v[46:47]
	v_pk_fma_f32 v[40:41], v[40:41], v[166:167], v[44:45]
	v_pk_mul_f32 v[34:35], v[36:37], v[36:37]
	v_pk_mul_f32 v[44:45], v[42:43], v[42:43]
	v_pk_fma_f32 v[34:35], v[38:39], v[38:39], v[34:35]
	v_pk_fma_f32 v[44:45], v[40:41], v[40:41], v[44:45]
	v_add_f32_e32 v34, v34, v35
	v_add_f32_e32 v35, v44, v45
	v_add_f32_e32 v34, v34, v35
	v_add_f32_e32 v44, v52, v34
	v_cvt_pk_bf16_f32 v34, v38, v39
	v_cvt_pk_bf16_f32 v35, v40, v41
	v_cvt_pk_bf16_f32 v36, v36, v37
	v_cvt_pk_bf16_f32 v37, v42, v43
	global_store_dwordx4 v[54:55], v[34:37], off offset:1024
	s_nop 1
	v_mov_b32_e32 v34, v44
	s_nop 1
	v_permlane16_swap_b32_e32 v44, v34
	v_add_f32_e32 v34, v44, v34
	v_mov_b32_e32 v35, v34
	s_nop 1
	v_permlane32_swap_b32_e32 v34, v35
	s_and_saveexec_b64 s[24:25], s[4:5]
	s_cbranch_execz .LBB0_325
	v_add_f32_e32 v36, v34, v35
	v_lshlrev_b64 v[34:35], 6, v[184:185]
	v_lshl_add_u64 v[34:35], s[22:23], 0, v[34:35]
	v_lshl_add_u64 v[34:35], s[2:3], 2, v[34:35]
	s_lshl_b32 s34, s40, 2
	v_lshl_add_u64 v[34:35], v[34:35], 0, s[34:35]
	v_add_co_u32_e32 v34, vcc, 0x2000, v34
	s_nop 1
	v_addc_co_u32_e32 v35, vcc, 0, v35, vcc
	global_store_dword v[34:35], v36, off offset:1024
; #define GAS __attribute__((address_space(1)))
; __device__ __forceinline__ unsigned pk_bf16(float lo, float hi) { typedef __bf16 bf2 __attribute__((ext_vector_type(2))); f32x2 v = {lo, hi}; bf2 b = __builtin_convertvector(v, bf2); return __builtin_bit_cast(unsigned, b); }
;     __device__ __forceinline__ void operator()(const f32x4 (&acc)[2][2][4][2], const Unit& u, int wr, int wc, int fr, int fq, int ui) const {
;     ...
;             for (int m = 0; m < 4; ++m) {
;                 const int row = row0 + ai * HALF + m * 16;
;                 float ss = 0.f;
; #pragma unroll
;                 for (int bj = 0; bj < 2; ++bj) {
;                     const u32x4 b = xb[m][bj];
;                     const f32x4 a0 = {__builtin_bit_cast(float, b.x << 16), __builtin_bit_cast(float, b.x & 0xffff0000u), __builtin_bit_cast(float, b.y << 16), __builtin_bit_cast(float, b.y & 0xffff0000u)};
;                     const f32x4 a1 = {__builtin_bit_cast(float, b.z << 16), __builtin_bit_cast(float, b.z & 0xffff0000u), __builtin_bit_cast(float, b.w << 16), __builtin_bit_cast(float, b.w & 0xffff0000u)};
;                     const f32x4 o0 = a0 + acc[ai][bj][m][0] * scale, o1 = a1 + acc[ai][bj][m][1] * scale;
;                     { const f32x4 q = o0 * o0 + o1 * o1; ss += (q[0] + q[1]) + (q[2] + q[3]); }
;                     u32x4 w; w.x = pk_bf16(o0[0], o0[1]); w.y = pk_bf16(o0[2], o0[3]); w.z = pk_bf16(o1[0], o1[1]); w.w = pk_bf16(o1[2], o1[3]);
;                     *(GAS u32x4*)(XBo + ((size_t)(2 * u.pm + ai) * 32 + 8 * u.pn + 4 * bj + wc) * 4096 + (wr * 64 + m * 16 + fr) * 32 + 8 * fq) = w;
;                 }
;                 { const unsigned sb = __builtin_bit_cast(unsigned, ss); auto r16 = __builtin_amdgcn_permlane16_swap(sb, sb, false, false);
;                   ss = __builtin_bit_cast(float, (unsigned)r16[0]) + __builtin_bit_cast(float, (unsigned)r16[1]);
;                   const unsigned sc = __builtin_bit_cast(unsigned, ss); auto r32 = __builtin_amdgcn_permlane32_swap(sc, sc, false, false);
;                   ss = __builtin_bit_cast(float, (unsigned)r32[0]) + __builtin_bit_cast(float, (unsigned)r32[1]); }
;                 if (fq == 0) ((GAS float*)SSP)[(size_t)row * 16 + u.pn * 4 + wc] = ss;
.LBB0_325:
	s_or_b64 exec, exec, s[24:25]
	v_lshlrev_b32_e32 v34, 16, v228
	v_and_b32_e32 v35, 0xffff0000, v228
	v_lshlrev_b32_e32 v38, 16, v230
	v_and_b32_e32 v39, 0xffff0000, v230
	v_lshlrev_b32_e32 v40, 16, v231
	v_and_b32_e32 v41, 0xffff0000, v231
	v_mov_b32_e32 v167, v166
	v_lshlrev_b32_e32 v36, 16, v229
	v_and_b32_e32 v37, 0xffff0000, v229
	v_pk_fma_f32 v[30:31], v[30:31], v[176:177], v[34:35]
	v_pk_fma_f32 v[34:35], v[28:29], v[166:167], v[40:41]
	v_pk_fma_f32 v[28:29], v[26:27], v[176:177], v[38:39]
	v_pk_fma_f32 v[32:33], v[32:33], v[166:167], v[36:37]
	v_pk_mul_f32 v[26:27], v[28:29], v[28:29]
	v_pk_mul_f32 v[36:37], v[34:35], v[34:35]
	v_pk_fma_f32 v[26:27], v[30:31], v[30:31], v[26:27]
	v_pk_fma_f32 v[36:37], v[32:33], v[32:33], v[36:37]
	v_add_f32_e32 v26, v26, v27
	v_add_f32_e32 v27, v36, v37
	v_add_f32_e32 v36, v26, v27
	v_cvt_pk_bf16_f32 v26, v30, v31
	v_cvt_pk_bf16_f32 v27, v32, v33
	v_cvt_pk_bf16_f32 v28, v28, v29
	v_cvt_pk_bf16_f32 v29, v34, v35
	global_store_dwordx4 v[58:59], v[26:29], off offset:2048
	v_lshlrev_b32_e32 v30, 16, v226
	v_and_b32_e32 v31, 0xffff0000, v226
	v_lshlrev_b32_e32 v26, 16, v224
	v_and_b32_e32 v27, 0xffff0000, v224
	v_lshlrev_b32_e32 v32, 16, v227
	v_and_b32_e32 v33, 0xffff0000, v227
	v_lshlrev_b32_e32 v28, 16, v225
	v_and_b32_e32 v29, 0xffff0000, v225
	v_pk_fma_f32 v[22:23], v[22:23], v[176:177], v[26:27]
	v_pk_fma_f32 v[26:27], v[20:21], v[166:167], v[32:33]
	v_pk_fma_f32 v[20:21], v[18:19], v[176:177], v[30:31]
	v_pk_fma_f32 v[24:25], v[24:25], v[166:167], v[28:29]
	v_pk_mul_f32 v[18:19], v[20:21], v[20:21]
	v_pk_mul_f32 v[28:29], v[26:27], v[26:27]
	v_pk_fma_f32 v[18:19], v[22:23], v[22:23], v[18:19]
	v_pk_fma_f32 v[28:29], v[24:25], v[24:25], v[28:29]
	v_add_f32_e32 v18, v18, v19
	v_add_f32_e32 v19, v28, v29
	v_add_f32_e32 v18, v18, v19
	v_add_f32_e32 v28, v36, v18
	v_cvt_pk_bf16_f32 v18, v22, v23
	v_cvt_pk_bf16_f32 v19, v24, v25
	v_cvt_pk_bf16_f32 v20, v20, v21
	v_cvt_pk_bf16_f32 v21, v26, v27
	global_store_dwordx4 v[54:55], v[18:21], off offset:2048
	s_nop 1
	v_mov_b32_e32 v18, v28
	s_nop 1
	v_permlane16_swap_b32_e32 v28, v18
	v_add_f32_e32 v18, v28, v18
	v_mov_b32_e32 v19, v18
	s_nop 1
	v_permlane32_swap_b32_e32 v18, v19
	s_and_saveexec_b64 s[24:25], s[4:5]
	s_cbranch_execz .LBB0_327
	v_add_f32_e32 v20, v18, v19
	v_lshlrev_b64 v[18:19], 6, v[184:185]
	v_lshl_add_u64 v[18:19], s[22:23], 0, v[18:19]
	v_lshl_add_u64 v[18:19], s[2:3], 2, v[18:19]
	s_lshl_b32 s34, s40, 2
	v_lshl_add_u64 v[18:19], v[18:19], 0, s[34:35]
	v_add_co_u32_e32 v18, vcc, 0x2000, v18
	s_nop 1
	v_addc_co_u32_e32 v19, vcc, 0, v19, vcc
	global_store_dword v[18:19], v20, off offset:2048
.LBB0_327:
	s_or_b64 exec, exec, s[24:25]
	v_lshlrev_b32_e32 v18, 16, v220
	v_and_b32_e32 v19, 0xffff0000, v220
	v_lshlrev_b32_e32 v22, 16, v222
	v_and_b32_e32 v23, 0xffff0000, v222
	v_lshlrev_b32_e32 v24, 16, v223
	v_and_b32_e32 v25, 0xffff0000, v223
	v_lshlrev_b32_e32 v20, 16, v221
	v_and_b32_e32 v21, 0xffff0000, v221
	v_pk_fma_f32 v[14:15], v[14:15], v[176:177], v[18:19]
	v_pk_fma_f32 v[18:19], v[12:13], v[166:167], v[24:25]
	v_pk_fma_f32 v[12:13], v[10:11], v[176:177], v[22:23]
	v_pk_fma_f32 v[16:17], v[16:17], v[166:167], v[20:21]
	v_pk_mul_f32 v[10:11], v[12:13], v[12:13]
	v_pk_mul_f32 v[20:21], v[18:19], v[18:19]
	v_pk_fma_f32 v[10:11], v[14:15], v[14:15], v[10:11]
	v_pk_fma_f32 v[20:21], v[16:17], v[16:17], v[20:21]
	v_add_f32_e32 v10, v10, v11
	v_add_f32_e32 v11, v20, v21
	v_add_f32_e32 v20, v10, v11
	v_cvt_pk_bf16_f32 v10, v14, v15
	v_cvt_pk_bf16_f32 v11, v16, v17
	v_cvt_pk_bf16_f32 v12, v12, v13
	v_cvt_pk_bf16_f32 v13, v18, v19
	global_store_dwordx4 v[58:59], v[10:13], off offset:3072
	v_lshlrev_b32_e32 v14, 16, v218
	v_and_b32_e32 v15, 0xffff0000, v218
	v_lshlrev_b32_e32 v10, 16, v216
	v_and_b32_e32 v11, 0xffff0000, v216
	v_lshlrev_b32_e32 v16, 16, v219
	v_and_b32_e32 v17, 0xffff0000, v219
	v_lshlrev_b32_e32 v12, 16, v217
	v_and_b32_e32 v13, 0xffff0000, v217
	v_pk_fma_f32 v[6:7], v[6:7], v[176:177], v[10:11]
	v_pk_fma_f32 v[10:11], v[4:5], v[166:167], v[16:17]
	v_pk_fma_f32 v[4:5], v[2:3], v[176:177], v[14:15]
	v_pk_fma_f32 v[8:9], v[8:9], v[166:167], v[12:13]
	v_pk_mul_f32 v[2:3], v[4:5], v[4:5]
	v_pk_mul_f32 v[12:13], v[10:11], v[10:11]
	v_pk_fma_f32 v[2:3], v[6:7], v[6:7], v[2:3]
	v_pk_fma_f32 v[12:13], v[8:9], v[8:9], v[12:13]
	v_add_f32_e32 v2, v2, v3
	v_add_f32_e32 v3, v12, v13
	v_add_f32_e32 v2, v2, v3
	v_add_f32_e32 v12, v20, v2
	v_cvt_pk_bf16_f32 v2, v6, v7
	v_cvt_pk_bf16_f32 v3, v8, v9
	v_cvt_pk_bf16_f32 v4, v4, v5
	v_cvt_pk_bf16_f32 v5, v10, v11
	global_store_dwordx4 v[54:55], v[2:5], off offset:3072
	s_nop 1
	v_mov_b32_e32 v2, v12
	s_nop 1
	v_permlane16_swap_b32_e32 v12, v2
	v_add_f32_e32 v2, v12, v2
	v_mov_b32_e32 v3, v2
	s_nop 1
	v_permlane32_swap_b32_e32 v2, v3
	s_and_saveexec_b64 s[24:25], s[4:5]
	s_cbranch_execz .LBB0_329
	v_add_f32_e32 v4, v2, v3
	v_lshlrev_b64 v[2:3], 6, v[184:185]
	v_lshl_add_u64 v[2:3], s[22:23], 0, v[2:3]
	v_lshl_add_u64 v[2:3], s[2:3], 2, v[2:3]
	s_lshl_b32 s34, s40, 2
	v_lshl_add_u64 v[2:3], v[2:3], 0, s[34:35]
	v_add_co_u32_e32 v2, vcc, 0x2000, v2
	s_nop 1
	v_addc_co_u32_e32 v3, vcc, 0, v3, vcc
	global_store_dword v[2:3], v4, off offset:3072
